# class B second pass takes [1536,4096) odd blocks (3 items): class A one item per wave, HGRN from 4608+g
# baseline (speedup 1.0000x reference)
;     ...
;     { int it = (PART == 0 ? gw : I_IN + gw); const int end = (PART == 0 ? I_IN : (I_IN + it_last < NITEMS ? I_IN + it_last : NITEMS));
;       if (it < end) {
;         ConvItem pa = conv_item(a, ws, it), pb = pa; float wa[32], wb[32]; f32x4 ka[2], kb[2];
;         conv_load(pa, wa, ka, lane);
;         for (;;) {
;             const bool hb = it + NGW < end; if (hb) { pb = conv_item(a, ws, it + NGW); conv_load(pb, wb, kb, lane); }
; __global__ void __launch_bounds__(NTHREADS, 2) hybrid_fwd(Args args) {
;     ...
;                 if (idx < 128) p0_prologue<1>(args, lds, wave, lane, idx * NWAVES + wave, 1024, 2048);
;                 else p0_prologue<1>(args, lds, wave, lane, 2048 + (idx - 128) * NWAVES + wave, 1024);
.LBB0_510:
	s_cmp_lg_u32 s99, 0
	s_cbranch_scc1 .Lmy_cv_done
	s_mov_b32 s99, 1
	s_movk_i32 s100, 0x1e00
	s_movk_i32 s101, 0x19ff
	s_lshl_b32 s0, s33, 3
	v_readlane_b32 s1, v254, 11
	s_add_i32 s0, s0, s1
	s_branch .Lmy_cv2
